# v68 + P1/P4b main loops: first iteration peeled with C=0 on each accumulator's first MFMA, 128 accumulator zero-init v_movs per unit removed
# speedup vs baseline: 1.0094x; 1.0058x over previous
.LBB0_142:
	s_ashr_i32 s77, s76, 31
	s_lshl_b64 s[14:15], s[76:77], 19
	s_add_u32 s78, s48, s14
	s_addc_u32 s79, s49, s15
	s_and_b64 s[14:15], s[12:13], exec
	s_cselect_b32 s77, s79, s1
	s_cselect_b32 vcc_lo, s78, s0
	s_ashr_i32 s75, s74, 31
	s_lshl_b64 s[14:15], s[74:75], 19
	s_add_u32 s80, s16, s14
	s_addc_u32 s81, s17, s15
	s_and_b64 s[14:15], s[12:13], exec
	s_cselect_b32 s75, s81, s85
	s_cselect_b32 vcc_hi, s80, s84
	s_add_u32 s0, s0, 0x40080
	s_addc_u32 s1, s1, 0
	s_add_u32 s14, s84, 0x100
	s_addc_u32 s15, s85, 0
	s_mov_b32 s89, -2
	ds_read_b128 v[96:99], v183
	ds_read_b128 v[100:103], v183 offset:1024
	ds_read_b128 v[112:115], v183 offset:2048
	ds_read_b128 v[120:123], v183 offset:3072
	ds_read_b128 v[144:147], v184
	ds_read_b128 v[170:173], v184 offset:1024
	ds_read_b128 v[186:189], v184 offset:2048
	ds_read_b128 v[190:193], v184 offset:3072
	s_add_u32 s44, s0, 0xfffc0080
	s_addc_u32 s45, s1, -1
	s_cmp_eq_u32 s89, 12
	s_cselect_b32 s87, s77, s45
	s_cselect_b32 s86, vcc_lo, s44
	s_cselect_b32 s85, s75, s15
	s_cselect_b32 s84, vcc_hi, s14
	v_lshl_add_u64 v[194:195], s[0:1], 0, v[162:163]
	s_add_i32 m0, s92, 0xc000
	ds_read_b128 v[198:201], v185
	ds_read_b128 v[206:209], v185 offset:1024
	ds_read_b128 v[210:213], v185 offset:2048
	ds_read_b128 v[214:217], v185 offset:3072
	ds_read_b128 v[218:221], v185 offset:4096
	ds_read_b128 v[222:225], v185 offset:5120
	ds_read_b128 v[226:229], v185 offset:6144
	ds_read_b128 v[230:233], v185 offset:7168
	global_load_lds_dwordx4 v[194:195], off
	v_lshl_add_u64 v[194:195], s[0:1], 0, v[164:165]
	s_add_i32 m0, s92, 0xe000
	s_nop 0
	global_load_lds_dwordx4 v[194:195], off
	s_waitcnt vmcnt(8)
	s_waitcnt lgkmcnt(0)
	s_barrier
	s_setprio 1
	s_waitcnt lgkmcnt(0)
	v_mfma_f32_16x16x32_bf16 v[140:143], v[96:99], v[198:201], 0
	v_mfma_f32_16x16x32_bf16 v[136:139], v[112:115], v[198:201], 0
	v_mfma_f32_16x16x32_bf16 v[124:127], v[96:99], v[210:213], 0
	v_mfma_f32_16x16x32_bf16 v[116:119], v[112:115], v[210:213], 0
	v_mfma_f32_16x16x32_bf16 v[92:95], v[96:99], v[218:221], 0
	v_mfma_f32_16x16x32_bf16 v[88:91], v[112:115], v[218:221], 0
	v_mfma_f32_16x16x32_bf16 v[76:79], v[96:99], v[226:229], 0
	v_mfma_f32_16x16x32_bf16 v[72:75], v[112:115], v[226:229], 0
	v_mfma_f32_16x16x32_bf16 v[140:143], v[100:103], v[206:209], v[140:143]
	v_mfma_f32_16x16x32_bf16 v[136:139], v[120:123], v[206:209], v[136:139]
	v_mfma_f32_16x16x32_bf16 v[124:127], v[100:103], v[214:217], v[124:127]
	v_mfma_f32_16x16x32_bf16 v[116:119], v[120:123], v[214:217], v[116:119]
	v_mfma_f32_16x16x32_bf16 v[92:95], v[100:103], v[222:225], v[92:95]
	v_mfma_f32_16x16x32_bf16 v[88:91], v[120:123], v[222:225], v[88:91]
	v_mfma_f32_16x16x32_bf16 v[76:79], v[100:103], v[230:233], v[76:79]
	v_mfma_f32_16x16x32_bf16 v[72:75], v[120:123], v[230:233], v[72:75]
	s_setprio 0
	s_setprio 1
	v_mfma_f32_16x16x32_bf16 v[128:131], v[144:147], v[198:201], 0
	v_mfma_f32_16x16x32_bf16 v[132:135], v[186:189], v[198:201], 0
	v_mfma_f32_16x16x32_bf16 v[104:107], v[144:147], v[210:213], 0
	v_mfma_f32_16x16x32_bf16 v[108:111], v[186:189], v[210:213], 0
	v_mfma_f32_16x16x32_bf16 v[80:83], v[144:147], v[218:221], 0
	v_mfma_f32_16x16x32_bf16 v[84:87], v[186:189], v[218:221], 0
	v_mfma_f32_16x16x32_bf16 v[64:67], v[144:147], v[226:229], 0
	v_mfma_f32_16x16x32_bf16 v[68:71], v[186:189], v[226:229], 0
	v_mfma_f32_16x16x32_bf16 v[128:131], v[170:173], v[206:209], v[128:131]
	v_mfma_f32_16x16x32_bf16 v[132:135], v[190:193], v[206:209], v[132:135]
	v_mfma_f32_16x16x32_bf16 v[104:107], v[170:173], v[214:217], v[104:107]
	v_mfma_f32_16x16x32_bf16 v[108:111], v[190:193], v[214:217], v[108:111]
	v_mfma_f32_16x16x32_bf16 v[80:83], v[170:173], v[222:225], v[80:83]
	v_mfma_f32_16x16x32_bf16 v[84:87], v[190:193], v[222:225], v[84:87]
	v_mfma_f32_16x16x32_bf16 v[64:67], v[170:173], v[230:233], v[64:67]
	v_mfma_f32_16x16x32_bf16 v[68:71], v[190:193], v[230:233], v[68:71]
	s_setprio 0
	s_barrier
	s_add_i32 s44, s56, s91
	v_lshl_add_u64 v[194:195], s[84:85], 0, v[150:151]
	s_mov_b32 m0, s44
	ds_read_b128 v[198:201], v185 offset:16384
	ds_read_b128 v[206:209], v185 offset:17408
	ds_read_b128 v[210:213], v185 offset:18432
	ds_read_b128 v[214:217], v185 offset:19456
	ds_read_b128 v[218:221], v185 offset:20480
	ds_read_b128 v[222:225], v185 offset:21504
	ds_read_b128 v[226:229], v185 offset:22528
	ds_read_b128 v[230:233], v185 offset:23552
	global_load_lds_dwordx4 v[194:195], off
	s_add_i32 m0, s44, 0x2000
	s_add_u32 s44, s84, 0x40000
	v_lshl_add_u64 v[234:235], s[84:85], 0, v[154:155]
	s_addc_u32 s45, s85, 0
	s_add_i32 s90, s57, s91
	global_load_lds_dwordx4 v[234:235], off
	v_lshl_add_u64 v[236:237], s[44:45], 0, v[150:151]
	s_mov_b32 m0, s90
	v_lshl_add_u64 v[238:239], s[86:87], 0, v[152:153]
	global_load_lds_dwordx4 v[236:237], off
	v_lshl_add_u64 v[236:237], s[44:45], 0, v[154:155]
	s_add_i32 m0, s90, 0x2000
	s_nop 0
	global_load_lds_dwordx4 v[236:237], off
	v_lshl_add_u64 v[236:237], s[86:87], 0, v[148:149]
	s_mov_b32 m0, s92
	s_nop 0
	global_load_lds_dwordx4 v[236:237], off
	s_mov_b32 m0, s93
	s_nop 0
	global_load_lds_dwordx4 v[238:239], off
	s_waitcnt vmcnt(8)
	s_waitcnt lgkmcnt(0)
	s_barrier
	s_setprio 1
	s_waitcnt lgkmcnt(0)
	v_mfma_f32_16x16x32_bf16 v[60:63], v[96:99], v[198:201], 0
	v_mfma_f32_16x16x32_bf16 v[56:59], v[112:115], v[198:201], 0
	v_mfma_f32_16x16x32_bf16 v[44:47], v[96:99], v[210:213], 0
	v_mfma_f32_16x16x32_bf16 v[40:43], v[112:115], v[210:213], 0
	v_mfma_f32_16x16x32_bf16 v[28:31], v[96:99], v[218:221], 0
	v_mfma_f32_16x16x32_bf16 v[24:27], v[112:115], v[218:221], 0
	v_mfma_f32_16x16x32_bf16 v[12:15], v[96:99], v[226:229], 0
	v_mfma_f32_16x16x32_bf16 v[8:11], v[112:115], v[226:229], 0
	v_mfma_f32_16x16x32_bf16 v[60:63], v[100:103], v[206:209], v[60:63]
	v_mfma_f32_16x16x32_bf16 v[56:59], v[120:123], v[206:209], v[56:59]
	v_mfma_f32_16x16x32_bf16 v[44:47], v[100:103], v[214:217], v[44:47]
	v_mfma_f32_16x16x32_bf16 v[40:43], v[120:123], v[214:217], v[40:43]
	v_mfma_f32_16x16x32_bf16 v[28:31], v[100:103], v[222:225], v[28:31]
	v_mfma_f32_16x16x32_bf16 v[24:27], v[120:123], v[222:225], v[24:27]
	v_mfma_f32_16x16x32_bf16 v[12:15], v[100:103], v[230:233], v[12:15]
	v_mfma_f32_16x16x32_bf16 v[8:11], v[120:123], v[230:233], v[8:11]
	s_setprio 0
	s_setprio 1
	v_mfma_f32_16x16x32_bf16 v[48:51], v[144:147], v[198:201], 0
	v_mfma_f32_16x16x32_bf16 v[52:55], v[186:189], v[198:201], 0
	v_mfma_f32_16x16x32_bf16 v[32:35], v[144:147], v[210:213], 0
	v_mfma_f32_16x16x32_bf16 v[36:39], v[186:189], v[210:213], 0
	v_mfma_f32_16x16x32_bf16 v[16:19], v[144:147], v[218:221], 0
	v_mfma_f32_16x16x32_bf16 v[20:23], v[186:189], v[218:221], 0
	v_mfma_f32_16x16x32_bf16 v[4:7], v[144:147], v[226:229], 0
	v_mfma_f32_16x16x32_bf16 v[0:3], v[186:189], v[226:229], 0
	v_mfma_f32_16x16x32_bf16 v[48:51], v[170:173], v[206:209], v[48:51]
	v_mfma_f32_16x16x32_bf16 v[52:55], v[190:193], v[206:209], v[52:55]
	v_mfma_f32_16x16x32_bf16 v[32:35], v[170:173], v[214:217], v[32:35]
	v_mfma_f32_16x16x32_bf16 v[36:39], v[190:193], v[214:217], v[36:39]
	v_mfma_f32_16x16x32_bf16 v[16:19], v[170:173], v[222:225], v[16:19]
	v_mfma_f32_16x16x32_bf16 v[20:23], v[190:193], v[222:225], v[20:23]
	v_mfma_f32_16x16x32_bf16 v[4:7], v[170:173], v[230:233], v[4:7]
	v_mfma_f32_16x16x32_bf16 v[0:3], v[190:193], v[230:233], v[0:3]
	s_setprio 0
	s_barrier
	s_add_i32 s90, 0, 0x18000
	s_add_i32 s33, 0, 0x1c000
	v_add_u32_e32 v120, s90, v175
	v_add_u32_e32 v190, s33, v175
	ds_read_b128 v[96:99], v120
	ds_read_b128 v[100:103], v120 offset:1024
	ds_read_b128 v[112:115], v120 offset:2048
	ds_read_b128 v[120:123], v120 offset:3072
	ds_read_b128 v[144:147], v190
	ds_read_b128 v[170:173], v190 offset:1024
	ds_read_b128 v[186:189], v190 offset:2048
	ds_read_b128 v[190:193], v190 offset:3072
	s_add_u32 s44, s86, 0x40000
	s_addc_u32 s45, s87, 0
	s_mov_b32 m0, s94
	v_lshl_add_u64 v[240:241], s[44:45], 0, v[148:149]
	ds_read_b128 v[198:201], v185 offset:32768
	ds_read_b128 v[206:209], v185 offset:33792
	ds_read_b128 v[210:213], v185 offset:34816
	ds_read_b128 v[214:217], v185 offset:35840
	ds_read_b128 v[218:221], v185 offset:36864
	ds_read_b128 v[222:225], v185 offset:37888
	ds_read_b128 v[226:229], v185 offset:38912
	ds_read_b128 v[230:233], v185 offset:39936
	global_load_lds_dwordx4 v[240:241], off
	v_lshl_add_u64 v[240:241], s[44:45], 0, v[152:153]
	s_mov_b32 m0, s95
	s_nop 0
	global_load_lds_dwordx4 v[240:241], off
	s_waitcnt vmcnt(8)
	s_waitcnt lgkmcnt(0)
	s_barrier
	s_setprio 1
	s_waitcnt lgkmcnt(0)
	v_mfma_f32_16x16x32_bf16 v[140:143], v[96:99], v[198:201], v[140:143]
	v_mfma_f32_16x16x32_bf16 v[136:139], v[112:115], v[198:201], v[136:139]
	v_mfma_f32_16x16x32_bf16 v[124:127], v[96:99], v[210:213], v[124:127]
	v_mfma_f32_16x16x32_bf16 v[116:119], v[112:115], v[210:213], v[116:119]
	v_mfma_f32_16x16x32_bf16 v[92:95], v[96:99], v[218:221], v[92:95]
	v_mfma_f32_16x16x32_bf16 v[88:91], v[112:115], v[218:221], v[88:91]
	v_mfma_f32_16x16x32_bf16 v[76:79], v[96:99], v[226:229], v[76:79]
	v_mfma_f32_16x16x32_bf16 v[72:75], v[112:115], v[226:229], v[72:75]
	v_mfma_f32_16x16x32_bf16 v[140:143], v[100:103], v[206:209], v[140:143]
	v_mfma_f32_16x16x32_bf16 v[136:139], v[120:123], v[206:209], v[136:139]
	v_mfma_f32_16x16x32_bf16 v[124:127], v[100:103], v[214:217], v[124:127]
	v_mfma_f32_16x16x32_bf16 v[116:119], v[120:123], v[214:217], v[116:119]
	v_mfma_f32_16x16x32_bf16 v[92:95], v[100:103], v[222:225], v[92:95]
	v_mfma_f32_16x16x32_bf16 v[88:91], v[120:123], v[222:225], v[88:91]
	v_mfma_f32_16x16x32_bf16 v[76:79], v[100:103], v[230:233], v[76:79]
	v_mfma_f32_16x16x32_bf16 v[72:75], v[120:123], v[230:233], v[72:75]
	s_setprio 0
	s_setprio 1
	v_mfma_f32_16x16x32_bf16 v[128:131], v[144:147], v[198:201], v[128:131]
	v_mfma_f32_16x16x32_bf16 v[132:135], v[186:189], v[198:201], v[132:135]
	v_mfma_f32_16x16x32_bf16 v[104:107], v[144:147], v[210:213], v[104:107]
	v_mfma_f32_16x16x32_bf16 v[108:111], v[186:189], v[210:213], v[108:111]
	v_mfma_f32_16x16x32_bf16 v[80:83], v[144:147], v[218:221], v[80:83]
	v_mfma_f32_16x16x32_bf16 v[84:87], v[186:189], v[218:221], v[84:87]
	v_mfma_f32_16x16x32_bf16 v[64:67], v[144:147], v[226:229], v[64:67]
	v_mfma_f32_16x16x32_bf16 v[68:71], v[186:189], v[226:229], v[68:71]
	v_mfma_f32_16x16x32_bf16 v[128:131], v[170:173], v[206:209], v[128:131]
	v_mfma_f32_16x16x32_bf16 v[132:135], v[190:193], v[206:209], v[132:135]
	v_mfma_f32_16x16x32_bf16 v[104:107], v[170:173], v[214:217], v[104:107]
	v_mfma_f32_16x16x32_bf16 v[108:111], v[190:193], v[214:217], v[108:111]
	v_mfma_f32_16x16x32_bf16 v[80:83], v[170:173], v[222:225], v[80:83]
	v_mfma_f32_16x16x32_bf16 v[84:87], v[190:193], v[222:225], v[84:87]
	v_mfma_f32_16x16x32_bf16 v[64:67], v[170:173], v[230:233], v[64:67]
	v_mfma_f32_16x16x32_bf16 v[68:71], v[190:193], v[230:233], v[68:71]
	s_setprio 0
	s_barrier
	s_add_i32 s44, s90, s91
	v_lshl_add_u64 v[194:195], v[194:195], 0, s[62:63]
	s_mov_b32 m0, s44
	ds_read_b128 v[198:201], v185 offset:49152
	ds_read_b128 v[206:209], v185 offset:50176
	ds_read_b128 v[210:213], v185 offset:51200
	ds_read_b128 v[214:217], v185 offset:52224
	ds_read_b128 v[218:221], v185 offset:53248
	ds_read_b128 v[222:225], v185 offset:54272
	ds_read_b128 v[226:229], v185 offset:55296
	ds_read_b128 v[230:233], v185 offset:56320
	global_load_lds_dwordx4 v[194:195], off
	s_add_i32 m0, s44, 0x2000
	s_add_u32 s44, s84, 0x40080
	v_lshl_add_u64 v[194:195], v[234:235], 0, s[62:63]
	s_addc_u32 s45, s85, 0
	s_add_i32 s33, s33, s91
	global_load_lds_dwordx4 v[194:195], off
	v_lshl_add_u64 v[194:195], s[44:45], 0, v[150:151]
	s_mov_b32 m0, s33
	s_nop 0
	global_load_lds_dwordx4 v[194:195], off
	v_lshl_add_u64 v[194:195], s[44:45], 0, v[154:155]
	s_add_i32 m0, s33, 0x2000
	s_nop 0
	global_load_lds_dwordx4 v[194:195], off
	v_lshl_add_u64 v[194:195], v[236:237], 0, s[62:63]
	s_mov_b32 m0, s97
	s_nop 0
	global_load_lds_dwordx4 v[194:195], off
	v_lshl_add_u64 v[194:195], v[238:239], 0, s[62:63]
	s_mov_b32 m0, s98
	s_nop 0
	global_load_lds_dwordx4 v[194:195], off
	s_waitcnt vmcnt(8)
	s_waitcnt lgkmcnt(0)
	s_barrier
	s_setprio 1
	s_waitcnt lgkmcnt(0)
	v_mfma_f32_16x16x32_bf16 v[60:63], v[96:99], v[198:201], v[60:63]
	v_mfma_f32_16x16x32_bf16 v[56:59], v[112:115], v[198:201], v[56:59]
	v_mfma_f32_16x16x32_bf16 v[44:47], v[96:99], v[210:213], v[44:47]
	v_mfma_f32_16x16x32_bf16 v[40:43], v[112:115], v[210:213], v[40:43]
	v_mfma_f32_16x16x32_bf16 v[28:31], v[96:99], v[218:221], v[28:31]
	v_mfma_f32_16x16x32_bf16 v[24:27], v[112:115], v[218:221], v[24:27]
	v_mfma_f32_16x16x32_bf16 v[12:15], v[96:99], v[226:229], v[12:15]
	v_mfma_f32_16x16x32_bf16 v[8:11], v[112:115], v[226:229], v[8:11]
	v_mfma_f32_16x16x32_bf16 v[60:63], v[100:103], v[206:209], v[60:63]
	v_mfma_f32_16x16x32_bf16 v[56:59], v[120:123], v[206:209], v[56:59]
	v_mfma_f32_16x16x32_bf16 v[44:47], v[100:103], v[214:217], v[44:47]
	v_mfma_f32_16x16x32_bf16 v[40:43], v[120:123], v[214:217], v[40:43]
	v_mfma_f32_16x16x32_bf16 v[28:31], v[100:103], v[222:225], v[28:31]
	v_mfma_f32_16x16x32_bf16 v[24:27], v[120:123], v[222:225], v[24:27]
	v_mfma_f32_16x16x32_bf16 v[12:15], v[100:103], v[230:233], v[12:15]
	v_mfma_f32_16x16x32_bf16 v[8:11], v[120:123], v[230:233], v[8:11]
	s_setprio 0
	s_setprio 1
	v_mfma_f32_16x16x32_bf16 v[48:51], v[144:147], v[198:201], v[48:51]
	v_mfma_f32_16x16x32_bf16 v[52:55], v[186:189], v[198:201], v[52:55]
	v_mfma_f32_16x16x32_bf16 v[32:35], v[144:147], v[210:213], v[32:35]
	v_mfma_f32_16x16x32_bf16 v[36:39], v[186:189], v[210:213], v[36:39]
	v_mfma_f32_16x16x32_bf16 v[16:19], v[144:147], v[218:221], v[16:19]
	v_mfma_f32_16x16x32_bf16 v[20:23], v[186:189], v[218:221], v[20:23]
	v_mfma_f32_16x16x32_bf16 v[4:7], v[144:147], v[226:229], v[4:7]
	v_mfma_f32_16x16x32_bf16 v[0:3], v[186:189], v[226:229], v[0:3]
	v_mfma_f32_16x16x32_bf16 v[48:51], v[170:173], v[206:209], v[48:51]
	v_mfma_f32_16x16x32_bf16 v[52:55], v[190:193], v[206:209], v[52:55]
	v_mfma_f32_16x16x32_bf16 v[32:35], v[170:173], v[214:217], v[32:35]
	v_mfma_f32_16x16x32_bf16 v[36:39], v[190:193], v[214:217], v[36:39]
	v_mfma_f32_16x16x32_bf16 v[16:19], v[170:173], v[222:225], v[16:19]
	v_mfma_f32_16x16x32_bf16 v[20:23], v[190:193], v[222:225], v[20:23]
	v_mfma_f32_16x16x32_bf16 v[4:7], v[170:173], v[230:233], v[4:7]
	v_mfma_f32_16x16x32_bf16 v[0:3], v[190:193], v[230:233], v[0:3]
	s_setprio 0
	s_barrier
	s_add_i32 s89, s89, 2
	s_add_u32 s0, s0, 0x100
	s_addc_u32 s1, s1, 0
	s_add_u32 s14, s14, 0x100
	s_addc_u32 s15, s15, 0
	s_cmp_gt_u32 s89, 13
	s_branch .LBB0_143

.LBB0_348:
	s_nop 0
	s_add_u32 s38, s52, 0x1800000
	s_addc_u32 s39, s53, 0
	s_add_u32 s74, s52, 0x1900000
	s_addc_u32 s75, s53, 0
	s_bitcmp0_b32 s2, 0
	s_cselect_b64 s[62:63], -1, 0
	s_and_b64 s[0:1], s[62:63], s[42:43]
	s_mov_b32 s23, 0
	s_andn2_b64 vcc, exec, s[0:1]
	v_and_b32_e32 v171, 15, v196
	v_lshrrev_b32_e32 v197, 4, v204
	v_cmp_eq_u32_e64 s[0:1], 63, v204
	s_waitcnt lgkmcnt(0)
	s_cbranch_vccnz .LBB0_355
	v_lshlrev_b32_e32 v0, 3, v197
	v_readlane_b32 s14, v242, 2
	v_mov_b32_e32 v1, 0
	v_mbcnt_hi_u32_b32 v9, -1, v205
	v_lshl_or_b32 v7, s14, 7, v0
	v_lshlrev_b32_e32 v0, 11, v171
	v_lshl_add_u64 v[2:3], s[40:41], 0, v[0:1]
	v_lshlrev_b32_e32 v0, 1, v7
	v_and_b32_e32 v11, 64, v9
	v_lshl_add_u64 v[2:3], v[2:3], 0, v[0:1]
	v_lshl_add_u64 v[4:5], s[36:37], 0, v[0:1]
	v_or_b32_e32 v0, 32, v7
	v_or_b32_e32 v6, 64, v7
	v_or_b32_e32 v8, 0x60, v7
	v_add_u32_e32 v7, -1, v9
	v_cmp_lt_i32_e32 vcc, v7, v11
	s_and_b32 s8, s97, 0x3ffffc0
	s_lshl_b32 s8, s8, 6
	v_cndmask_b32_e32 v7, v7, v9, vcc
	v_lshlrev_b32_e32 v13, 2, v7
	v_add_u32_e32 v7, -2, v9
	v_cmp_lt_i32_e32 vcc, v7, v11
	v_lshl_or_b32 v19, v197, 8, s8
	s_lshl_b32 s8, s14, 3
	v_cndmask_b32_e32 v7, v7, v9, vcc
	v_lshlrev_b32_e32 v14, 2, v7
	v_add_u32_e32 v7, -4, v9
	v_cmp_lt_i32_e32 vcc, v7, v11
	s_lshl_b32 s22, s14, 1
	s_add_i32 s9, s8, 0
	v_cndmask_b32_e32 v7, v7, v9, vcc
	v_lshlrev_b32_e32 v15, 2, v7
	v_add_u32_e32 v7, -8, v9
	v_cmp_lt_i32_e32 vcc, v7, v11
	v_lshl_add_u32 v10, v171, 2, 0
	s_add_u32 s42, s50, s8
	v_cndmask_b32_e32 v7, v7, v9, vcc
	v_lshlrev_b32_e32 v16, 2, v7
	v_add_u32_e32 v7, -16, v9
	v_cmp_lt_i32_e32 vcc, v7, v11
	s_addc_u32 s43, s51, 0
	s_lshl_b64 s[46:47], s[22:23], 16
	v_cndmask_b32_e32 v7, v7, v9, vcc
	v_lshlrev_b32_e32 v17, 2, v7
	v_subrev_u32_e32 v7, 32, v9
	v_cmp_lt_i32_e32 vcc, v7, v11
	s_or_b32 s22, s22, 1
	v_add_u32_e32 v19, v10, v19
	v_cndmask_b32_e32 v7, v7, v9, vcc
	v_lshl_add_u32 v12, v204, 6, s9
	v_cmp_eq_u32_e64 s[8:9], 0, v204
	v_cmp_gt_u32_e64 s[10:11], 2, v204
	v_cmp_gt_u32_e64 s[12:13], 4, v204
	v_cmp_gt_u32_e64 s[16:17], 8, v204
	v_cmp_gt_u32_e64 s[18:19], 16, v204
	v_lshlrev_b32_e32 v18, 2, v7
	v_cmp_gt_u32_e64 s[20:21], 32, v204
	s_lshl_b32 s14, s14, 9
	s_lshl_b64 s[48:49], s[22:23], 16
	s_lshl_b32 s56, s54, 6
	v_lshlrev_b32_e32 v0, 1, v0
	v_lshlrev_b32_e32 v6, 1, v6
	v_mov_b32_e32 v7, v1
	v_lshlrev_b32_e32 v8, 1, v8
	v_mov_b32_e32 v9, v1
	v_mov_b32_e32 v20, 0x358637bd
	s_mov_b32 s57, 0xf800000
	v_mov_b32_e32 v21, 0x260
	s_mov_b32 s64, 0xbfb8aa3b
	v_add_u32_e32 v22, 0x400, v19
	v_add_u32_e32 v23, 0x800, v19
	v_add_u32_e32 v24, 0xc00, v19
	s_and_b32 s65, s2, 7
	s_lshl_b32 s65, s65, 3
	s_bfe_u32 s15, s2, 0x30003
	s_add_i32 s65, s65, s15
	s_lshl_b32 s65, s65, 2
	s_lshr_b32 s15, s2, 6
	s_add_i32 s65, s65, s15
	s_lshl_b32 s15, s65, 6
	s_branch .LBB0_351

.LBB0_373:
	s_ashr_i32 s23, s22, 31
	s_lshl_b64 s[14:15], s[22:23], 19
	s_add_u32 s64, s36, s14
	s_addc_u32 s65, s37, s15
	s_and_b64 s[14:15], s[8:9], exec
	s_cselect_b32 s11, s65, s69
	s_cselect_b32 s13, s64, s68
	s_ashr_i32 s21, s20, 31
	s_lshl_b64 s[14:15], s[20:21], 19
	s_add_u32 s66, s58, s14
	s_addc_u32 s67, s59, s15
	s_and_b64 s[14:15], s[8:9], exec
	s_cselect_b32 s21, s67, s71
	s_cselect_b32 s23, s66, s70
	s_add_u32 s68, s68, 0x40080
	s_addc_u32 s69, s69, 0
	s_add_u32 s14, s70, 0x100
	s_addc_u32 s15, s71, 0
	s_mov_b32 s56, -2
	ds_read_b128 v[32:35], v208
	ds_read_b128 v[36:39], v208 offset:1024
	ds_read_b128 v[40:43], v208 offset:2048
	ds_read_b128 v[44:47], v208 offset:3072
	ds_read_b128 v[144:147], v209
	ds_read_b128 v[148:151], v209 offset:1024
	ds_read_b128 v[152:155], v209 offset:2048
	ds_read_b128 v[156:159], v209 offset:3072
	s_add_u32 s33, s68, 0xfffc0080
	s_addc_u32 s57, s69, -1
	s_cmp_eq_u32 s56, 12
	s_cselect_b32 s73, s11, s57
	s_cselect_b32 s72, s13, s33
	s_cselect_b32 s71, s21, s15
	s_cselect_b32 s70, s23, s14
	v_lshl_add_u64 v[194:195], s[68:69], 0, v[174:175]
	s_add_i32 m0, s77, 0xc000
	ds_read_b128 v[182:185], v210
	ds_read_b128 v[186:189], v210 offset:1024
	ds_read_b128 v[190:193], v210 offset:2048
	ds_read_b128 v[198:201], v210 offset:3072
	ds_read_b128 v[214:217], v210 offset:4096
	ds_read_b128 v[218:221], v210 offset:5120
	ds_read_b128 v[222:225], v210 offset:6144
	ds_read_b128 v[226:229], v210 offset:7168
	global_load_lds_dwordx4 v[194:195], off
	v_lshl_add_u64 v[194:195], s[68:69], 0, v[176:177]
	s_add_i32 m0, s77, 0xe000
	s_nop 0
	global_load_lds_dwordx4 v[194:195], off
	s_waitcnt vmcnt(8)
	s_waitcnt lgkmcnt(0)
	s_barrier
	s_setprio 1
	s_waitcnt lgkmcnt(0)
	v_mfma_f32_16x16x32_bf16 v[140:143], v[32:35], v[182:185], 0
	v_mfma_f32_16x16x32_bf16 v[136:139], v[40:43], v[182:185], 0
	v_mfma_f32_16x16x32_bf16 v[124:127], v[32:35], v[190:193], 0
	v_mfma_f32_16x16x32_bf16 v[120:123], v[40:43], v[190:193], 0
	v_mfma_f32_16x16x32_bf16 v[108:111], v[32:35], v[214:217], 0
	v_mfma_f32_16x16x32_bf16 v[104:107], v[40:43], v[214:217], 0
	v_mfma_f32_16x16x32_bf16 v[92:95], v[32:35], v[222:225], 0
	v_mfma_f32_16x16x32_bf16 v[88:91], v[40:43], v[222:225], 0
	v_mfma_f32_16x16x32_bf16 v[140:143], v[36:39], v[186:189], v[140:143]
	v_mfma_f32_16x16x32_bf16 v[136:139], v[44:47], v[186:189], v[136:139]
	v_mfma_f32_16x16x32_bf16 v[124:127], v[36:39], v[198:201], v[124:127]
	v_mfma_f32_16x16x32_bf16 v[120:123], v[44:47], v[198:201], v[120:123]
	v_mfma_f32_16x16x32_bf16 v[108:111], v[36:39], v[218:221], v[108:111]
	v_mfma_f32_16x16x32_bf16 v[104:107], v[44:47], v[218:221], v[104:107]
	v_mfma_f32_16x16x32_bf16 v[92:95], v[36:39], v[226:229], v[92:95]
	v_mfma_f32_16x16x32_bf16 v[88:91], v[44:47], v[226:229], v[88:91]
	s_setprio 0
	s_setprio 1
	v_mfma_f32_16x16x32_bf16 v[132:135], v[144:147], v[182:185], 0
	v_mfma_f32_16x16x32_bf16 v[128:131], v[152:155], v[182:185], 0
	v_mfma_f32_16x16x32_bf16 v[116:119], v[144:147], v[190:193], 0
	v_mfma_f32_16x16x32_bf16 v[112:115], v[152:155], v[190:193], 0
	v_mfma_f32_16x16x32_bf16 v[100:103], v[144:147], v[214:217], 0
	v_mfma_f32_16x16x32_bf16 v[96:99], v[152:155], v[214:217], 0
	v_mfma_f32_16x16x32_bf16 v[84:87], v[144:147], v[222:225], 0
	v_mfma_f32_16x16x32_bf16 v[80:83], v[152:155], v[222:225], 0
	v_mfma_f32_16x16x32_bf16 v[132:135], v[148:151], v[186:189], v[132:135]
	v_mfma_f32_16x16x32_bf16 v[128:131], v[156:159], v[186:189], v[128:131]
	v_mfma_f32_16x16x32_bf16 v[116:119], v[148:151], v[198:201], v[116:119]
	v_mfma_f32_16x16x32_bf16 v[112:115], v[156:159], v[198:201], v[112:115]
	v_mfma_f32_16x16x32_bf16 v[100:103], v[148:151], v[218:221], v[100:103]
	v_mfma_f32_16x16x32_bf16 v[96:99], v[156:159], v[218:221], v[96:99]
	v_mfma_f32_16x16x32_bf16 v[84:87], v[148:151], v[226:229], v[84:87]
	v_mfma_f32_16x16x32_bf16 v[80:83], v[156:159], v[226:229], v[80:83]
	s_setprio 0
	s_barrier
	s_add_i32 s33, s87, s76
	v_lshl_add_u64 v[194:195], s[70:71], 0, v[162:163]
	s_mov_b32 m0, s33
	ds_read_b128 v[182:185], v210 offset:16384
	ds_read_b128 v[186:189], v210 offset:17408
	ds_read_b128 v[190:193], v210 offset:18432
	ds_read_b128 v[198:201], v210 offset:19456
	ds_read_b128 v[214:217], v210 offset:20480
	ds_read_b128 v[218:221], v210 offset:21504
	ds_read_b128 v[222:225], v210 offset:22528
	ds_read_b128 v[226:229], v210 offset:23552
	global_load_lds_dwordx4 v[194:195], off
	s_add_i32 m0, s33, 0x2000
	s_add_u32 s88, s70, 0x40000
	v_lshl_add_u64 v[230:231], s[70:71], 0, v[166:167]
	s_addc_u32 s89, s71, 0
	s_add_i32 s33, s91, s76
	global_load_lds_dwordx4 v[230:231], off
	v_lshl_add_u64 v[232:233], s[88:89], 0, v[162:163]
	s_mov_b32 m0, s33
	v_lshl_add_u64 v[234:235], s[72:73], 0, v[164:165]
	global_load_lds_dwordx4 v[232:233], off
	v_lshl_add_u64 v[232:233], s[88:89], 0, v[166:167]
	s_add_i32 m0, s33, 0x2000
	s_nop 0
	global_load_lds_dwordx4 v[232:233], off
	v_lshl_add_u64 v[232:233], s[72:73], 0, v[160:161]
	s_mov_b32 m0, s77
	s_nop 0
	global_load_lds_dwordx4 v[232:233], off
	s_mov_b32 m0, s78
	s_nop 0
	global_load_lds_dwordx4 v[234:235], off
	s_waitcnt vmcnt(8)
	s_waitcnt lgkmcnt(0)
	s_barrier
	s_setprio 1
	s_waitcnt lgkmcnt(0)
	v_mfma_f32_16x16x32_bf16 v[76:79], v[32:35], v[182:185], 0
	v_mfma_f32_16x16x32_bf16 v[72:75], v[40:43], v[182:185], 0
	v_mfma_f32_16x16x32_bf16 v[60:63], v[32:35], v[190:193], 0
	v_mfma_f32_16x16x32_bf16 v[56:59], v[40:43], v[190:193], 0
	v_mfma_f32_16x16x32_bf16 v[28:31], v[32:35], v[214:217], 0
	v_mfma_f32_16x16x32_bf16 v[24:27], v[40:43], v[214:217], 0
	v_mfma_f32_16x16x32_bf16 v[12:15], v[32:35], v[222:225], 0
	v_mfma_f32_16x16x32_bf16 v[8:11], v[40:43], v[222:225], 0
	v_mfma_f32_16x16x32_bf16 v[76:79], v[36:39], v[186:189], v[76:79]
	v_mfma_f32_16x16x32_bf16 v[72:75], v[44:47], v[186:189], v[72:75]
	v_mfma_f32_16x16x32_bf16 v[60:63], v[36:39], v[198:201], v[60:63]
	v_mfma_f32_16x16x32_bf16 v[56:59], v[44:47], v[198:201], v[56:59]
	v_mfma_f32_16x16x32_bf16 v[28:31], v[36:39], v[218:221], v[28:31]
	v_mfma_f32_16x16x32_bf16 v[24:27], v[44:47], v[218:221], v[24:27]
	v_mfma_f32_16x16x32_bf16 v[12:15], v[36:39], v[226:229], v[12:15]
	v_mfma_f32_16x16x32_bf16 v[8:11], v[44:47], v[226:229], v[8:11]
	s_setprio 0
	s_setprio 1
	v_mfma_f32_16x16x32_bf16 v[20:23], v[144:147], v[214:217], 0
	v_mfma_f32_16x16x32_bf16 v[16:19], v[152:155], v[214:217], 0
	v_mfma_f32_16x16x32_bf16 v[4:7], v[144:147], v[222:225], 0
	v_mfma_f32_16x16x32_bf16 v[0:3], v[152:155], v[222:225], 0
	v_mfma_f32_16x16x32_bf16 v[32:35], v[144:147], v[182:185], 0
	v_mfma_f32_16x16x32_bf16 v[36:39], v[152:155], v[182:185], 0
	v_mfma_f32_16x16x32_bf16 v[40:43], v[144:147], v[190:193], 0
	v_mfma_f32_16x16x32_bf16 v[44:47], v[152:155], v[190:193], 0
	v_mfma_f32_16x16x32_bf16 v[20:23], v[148:151], v[218:221], v[20:23]
	v_mfma_f32_16x16x32_bf16 v[16:19], v[156:159], v[218:221], v[16:19]
	v_mfma_f32_16x16x32_bf16 v[4:7], v[148:151], v[226:229], v[4:7]
	v_mfma_f32_16x16x32_bf16 v[0:3], v[156:159], v[226:229], v[0:3]
	v_mfma_f32_16x16x32_bf16 v[32:35], v[148:151], v[186:189], v[32:35]
	v_mfma_f32_16x16x32_bf16 v[36:39], v[156:159], v[186:189], v[36:39]
	v_mfma_f32_16x16x32_bf16 v[40:43], v[148:151], v[198:201], v[40:43]
	v_mfma_f32_16x16x32_bf16 v[44:47], v[156:159], v[198:201], v[44:47]
	s_setprio 0
	s_barrier
	s_add_i32 s33, 0, 0x18000
	s_add_i32 s57, 0, 0x1c000
	v_add_u32_e32 v68, s33, v207
	v_add_u32_e32 v156, s57, v207
	ds_read_b128 v[48:51], v68
	ds_read_b128 v[52:55], v68 offset:1024
	ds_read_b128 v[64:67], v68 offset:2048
	ds_read_b128 v[68:71], v68 offset:3072
	ds_read_b128 v[144:147], v156
	ds_read_b128 v[148:151], v156 offset:1024
	ds_read_b128 v[152:155], v156 offset:2048
	ds_read_b128 v[156:159], v156 offset:3072
	s_add_u32 s72, s72, 0x40000
	s_addc_u32 s73, s73, 0
	s_mov_b32 m0, s79
	v_lshl_add_u64 v[236:237], s[72:73], 0, v[160:161]
	ds_read_b128 v[182:185], v210 offset:32768
	ds_read_b128 v[186:189], v210 offset:33792
	ds_read_b128 v[190:193], v210 offset:34816
	ds_read_b128 v[198:201], v210 offset:35840
	ds_read_b128 v[214:217], v210 offset:36864
	ds_read_b128 v[218:221], v210 offset:37888
	ds_read_b128 v[222:225], v210 offset:38912
	ds_read_b128 v[226:229], v210 offset:39936
	global_load_lds_dwordx4 v[236:237], off
	v_lshl_add_u64 v[236:237], s[72:73], 0, v[164:165]
	s_mov_b32 m0, s82
	s_nop 0
	global_load_lds_dwordx4 v[236:237], off
	s_waitcnt vmcnt(8)
	s_waitcnt lgkmcnt(0)
	s_barrier
	s_setprio 1
	s_waitcnt lgkmcnt(0)
	v_mfma_f32_16x16x32_bf16 v[140:143], v[48:51], v[182:185], v[140:143]
	v_mfma_f32_16x16x32_bf16 v[136:139], v[64:67], v[182:185], v[136:139]
	v_mfma_f32_16x16x32_bf16 v[124:127], v[48:51], v[190:193], v[124:127]
	v_mfma_f32_16x16x32_bf16 v[120:123], v[64:67], v[190:193], v[120:123]
	v_mfma_f32_16x16x32_bf16 v[108:111], v[48:51], v[214:217], v[108:111]
	v_mfma_f32_16x16x32_bf16 v[104:107], v[64:67], v[214:217], v[104:107]
	v_mfma_f32_16x16x32_bf16 v[92:95], v[48:51], v[222:225], v[92:95]
	v_mfma_f32_16x16x32_bf16 v[88:91], v[64:67], v[222:225], v[88:91]
	v_mfma_f32_16x16x32_bf16 v[140:143], v[52:55], v[186:189], v[140:143]
	v_mfma_f32_16x16x32_bf16 v[136:139], v[68:71], v[186:189], v[136:139]
	v_mfma_f32_16x16x32_bf16 v[124:127], v[52:55], v[198:201], v[124:127]
	v_mfma_f32_16x16x32_bf16 v[120:123], v[68:71], v[198:201], v[120:123]
	v_mfma_f32_16x16x32_bf16 v[108:111], v[52:55], v[218:221], v[108:111]
	v_mfma_f32_16x16x32_bf16 v[104:107], v[68:71], v[218:221], v[104:107]
	v_mfma_f32_16x16x32_bf16 v[92:95], v[52:55], v[226:229], v[92:95]
	v_mfma_f32_16x16x32_bf16 v[88:91], v[68:71], v[226:229], v[88:91]
	s_setprio 0
	s_setprio 1
	v_mfma_f32_16x16x32_bf16 v[132:135], v[144:147], v[182:185], v[132:135]
	v_mfma_f32_16x16x32_bf16 v[128:131], v[152:155], v[182:185], v[128:131]
	v_mfma_f32_16x16x32_bf16 v[116:119], v[144:147], v[190:193], v[116:119]
	v_mfma_f32_16x16x32_bf16 v[112:115], v[152:155], v[190:193], v[112:115]
	v_mfma_f32_16x16x32_bf16 v[100:103], v[144:147], v[214:217], v[100:103]
	v_mfma_f32_16x16x32_bf16 v[96:99], v[152:155], v[214:217], v[96:99]
	v_mfma_f32_16x16x32_bf16 v[84:87], v[144:147], v[222:225], v[84:87]
	v_mfma_f32_16x16x32_bf16 v[80:83], v[152:155], v[222:225], v[80:83]
	v_mfma_f32_16x16x32_bf16 v[132:135], v[148:151], v[186:189], v[132:135]
	v_mfma_f32_16x16x32_bf16 v[128:131], v[156:159], v[186:189], v[128:131]
	v_mfma_f32_16x16x32_bf16 v[116:119], v[148:151], v[198:201], v[116:119]
	v_mfma_f32_16x16x32_bf16 v[112:115], v[156:159], v[198:201], v[112:115]
	v_mfma_f32_16x16x32_bf16 v[100:103], v[148:151], v[218:221], v[100:103]
	v_mfma_f32_16x16x32_bf16 v[96:99], v[156:159], v[218:221], v[96:99]
	v_mfma_f32_16x16x32_bf16 v[84:87], v[148:151], v[226:229], v[84:87]
	v_mfma_f32_16x16x32_bf16 v[80:83], v[156:159], v[226:229], v[80:83]
	s_setprio 0
	s_barrier
	s_add_i32 s33, s33, s76
	v_lshl_add_u64 v[194:195], v[194:195], 0, s[16:17]
	s_mov_b32 m0, s33
	ds_read_b128 v[182:185], v210 offset:49152
	ds_read_b128 v[186:189], v210 offset:50176
	ds_read_b128 v[190:193], v210 offset:51200
	ds_read_b128 v[198:201], v210 offset:52224
	ds_read_b128 v[214:217], v210 offset:53248
	ds_read_b128 v[218:221], v210 offset:54272
	ds_read_b128 v[222:225], v210 offset:55296
	ds_read_b128 v[226:229], v210 offset:56320
	global_load_lds_dwordx4 v[194:195], off
	s_add_i32 m0, s33, 0x2000
	s_add_u32 s70, s70, 0x40080
	v_lshl_add_u64 v[194:195], v[230:231], 0, s[16:17]
	s_addc_u32 s71, s71, 0
	s_add_i32 s33, s57, s76
	global_load_lds_dwordx4 v[194:195], off
	v_lshl_add_u64 v[194:195], s[70:71], 0, v[162:163]
	s_mov_b32 m0, s33
	s_nop 0
	global_load_lds_dwordx4 v[194:195], off
	v_lshl_add_u64 v[194:195], s[70:71], 0, v[166:167]
	s_add_i32 m0, s33, 0x2000
	s_nop 0
	global_load_lds_dwordx4 v[194:195], off
	v_lshl_add_u64 v[194:195], v[232:233], 0, s[16:17]
	s_mov_b32 m0, s85
	s_nop 0
	global_load_lds_dwordx4 v[194:195], off
	v_lshl_add_u64 v[194:195], v[234:235], 0, s[16:17]
	s_mov_b32 m0, s86
	s_nop 0
	global_load_lds_dwordx4 v[194:195], off
	s_waitcnt vmcnt(8)
	s_waitcnt lgkmcnt(0)
	s_barrier
	s_setprio 1
	s_waitcnt lgkmcnt(0)
	v_mfma_f32_16x16x32_bf16 v[76:79], v[48:51], v[182:185], v[76:79]
	v_mfma_f32_16x16x32_bf16 v[72:75], v[64:67], v[182:185], v[72:75]
	v_mfma_f32_16x16x32_bf16 v[60:63], v[48:51], v[190:193], v[60:63]
	v_mfma_f32_16x16x32_bf16 v[56:59], v[64:67], v[190:193], v[56:59]
	v_mfma_f32_16x16x32_bf16 v[28:31], v[48:51], v[214:217], v[28:31]
	v_mfma_f32_16x16x32_bf16 v[24:27], v[64:67], v[214:217], v[24:27]
	v_mfma_f32_16x16x32_bf16 v[12:15], v[48:51], v[222:225], v[12:15]
	v_mfma_f32_16x16x32_bf16 v[8:11], v[64:67], v[222:225], v[8:11]
	v_mfma_f32_16x16x32_bf16 v[76:79], v[52:55], v[186:189], v[76:79]
	v_mfma_f32_16x16x32_bf16 v[72:75], v[68:71], v[186:189], v[72:75]
	v_mfma_f32_16x16x32_bf16 v[60:63], v[52:55], v[198:201], v[60:63]
	v_mfma_f32_16x16x32_bf16 v[56:59], v[68:71], v[198:201], v[56:59]
	v_mfma_f32_16x16x32_bf16 v[28:31], v[52:55], v[218:221], v[28:31]
	v_mfma_f32_16x16x32_bf16 v[24:27], v[68:71], v[218:221], v[24:27]
	v_mfma_f32_16x16x32_bf16 v[12:15], v[52:55], v[226:229], v[12:15]
	v_mfma_f32_16x16x32_bf16 v[8:11], v[68:71], v[226:229], v[8:11]
	s_setprio 0
	s_setprio 1
	v_mfma_f32_16x16x32_bf16 v[32:35], v[144:147], v[182:185], v[32:35]
	v_mfma_f32_16x16x32_bf16 v[68:71], v[148:151], v[186:189], v[32:35]
	v_mfma_f32_16x16x32_bf16 v[32:35], v[152:155], v[182:185], v[36:39]
	v_mfma_f32_16x16x32_bf16 v[64:67], v[156:159], v[186:189], v[32:35]
	v_mfma_f32_16x16x32_bf16 v[32:35], v[144:147], v[190:193], v[40:43]
	v_mfma_f32_16x16x32_bf16 v[52:55], v[148:151], v[198:201], v[32:35]
	v_mfma_f32_16x16x32_bf16 v[32:35], v[152:155], v[190:193], v[44:47]
	v_mfma_f32_16x16x32_bf16 v[20:23], v[144:147], v[214:217], v[20:23]
	v_mfma_f32_16x16x32_bf16 v[16:19], v[152:155], v[214:217], v[16:19]
	v_mfma_f32_16x16x32_bf16 v[4:7], v[144:147], v[222:225], v[4:7]
	v_mfma_f32_16x16x32_bf16 v[0:3], v[152:155], v[222:225], v[0:3]
	v_mfma_f32_16x16x32_bf16 v[48:51], v[156:159], v[198:201], v[32:35]
	v_mfma_f32_16x16x32_bf16 v[20:23], v[148:151], v[218:221], v[20:23]
	v_mfma_f32_16x16x32_bf16 v[16:19], v[156:159], v[218:221], v[16:19]
	v_mfma_f32_16x16x32_bf16 v[4:7], v[148:151], v[226:229], v[4:7]
	v_mfma_f32_16x16x32_bf16 v[0:3], v[156:159], v[226:229], v[0:3]
	s_setprio 0
	s_barrier
	s_add_i32 s56, s56, 2
	s_add_u32 s68, s68, 0x100
	s_addc_u32 s69, s69, 0
	s_add_u32 s14, s14, 0x100
	s_addc_u32 s15, s15, 0
	s_cmp_gt_u32 s56, 13
	s_branch .LBB0_374
